# grid barrier: the first arriver of an XCD also starts an L2 write-back (not waited for) so the last arriver's write-back finds less dirty data
# baseline (speedup 1.0000x reference)
; DI void grid_barrier(unsigned* ctr, unsigned target) {
;   __syncthreads();
;   if (threadIdx.x == 0) {
;     __threadfence();
;     __hip_atomic_fetch_add(ctr, 1u, __ATOMIC_RELAXED, __HIP_MEMORY_SCOPE_AGENT);
;     unsigned spins = 0;
;     while (__hip_atomic_load(ctr, __ATOMIC_RELAXED, __HIP_MEMORY_SCOPE_AGENT) < target && spins < (1u << 26)) { __builtin_amdgcn_s_sleep(2); ++spins; }
;     __threadfence();
;   }
;   __syncthreads();
; }
.Lg3_real:
	v_readlane_b32 s10, v252, 10
	v_readlane_b32 s11, v252, 11
	s_sub_u32 s14, s33, s10
	s_add_u32 s14, s14, 7
	s_lshr_b32 s14, s14, 3
	s_sub_u32 s15, s4, 1
	s_mul_i32 s11, s11, s15
	s_add_u32 s11, s11, s14
	s_lshl_b32 s10, s10, 7
	s_add_u32 s22, s24, s10
	s_addc_u32 s23, s25, 0
	global_atomic_add v1, v131, v0, s[22:23] offset:256 sc0
	s_waitcnt vmcnt(0)
	v_add_u32_e32 v1, 1, v1
	v_cmp_eq_u32_e32 vcc, s11, v1
	s_mov_b32 s10, 0
	s_cbranch_vccz .Lg3_nl
	buffer_wbl2 sc1
	s_waitcnt vmcnt(0)
	global_atomic_add v131, v0, s[24:25] offset:-1792
	global_atomic_add v131, v0, s[24:25] offset:-1664
	global_atomic_add v131, v0, s[24:25] offset:-1536
	global_atomic_add v131, v0, s[24:25] offset:-1408
	global_atomic_add v131, v0, s[24:25] offset:-1280
	global_atomic_add v131, v0, s[24:25] offset:-1152
	global_atomic_add v131, v0, s[24:25] offset:-1024
	global_atomic_add v131, v0, s[24:25] offset:-896
	s_branch .Lg3_w2
.Lg3_nl:
	v_readlane_b32 s14, v252, 11
	s_sub_u32 s14, s11, s14
	s_add_u32 s14, s14, 1
	v_cmp_eq_u32_e32 vcc, s14, v1
	s_cbranch_vccz .Lg3_w2
	buffer_wbl2 sc1
